# softmax segment reordered (tile staging first, shorter MFMA-result wait), K tile loads from scalar base + 32-bit lane offsets
# speedup vs baseline: 1.1277x; 1.0122x over previous
; __device__ __forceinline__ int swap23(int p) { return (p & ~12) | ((p & 4) << 1) | ((p & 8) >> 1); }
; #define A_STORE(buf) do { LAS unsigned char* bb = lds + (buf) * ABUF; \
;         *(LAS u32x4*)(bb + kr1 * KT_PITCH + kc1 * 16) = st[0]; *(LAS u32x4*)(bb + kr2 * KT_PITCH + kc2 * 16) = st[1]; *(LAS u32x4*)(bb + kr3 * KT_PITCH + kc3 * 16) = st[2]; \
;         *(LAS u32x4*)(bb + KT_BYTES + vd1 * VT_PITCH + vc * 16) = st[3]; *(LAS u32x4*)(bb + KT_BYTES + vd2 * VT_PITCH + vc * 16) = st[4]; } while (0)
; __device__ __forceinline__ void attn_unit(KParams& P, int l, const AUnit& U, LAS unsigned char* lds) {
;     ...
;     const int kr1 = tid / 20, kc1 = tid % 20, kr2 = (tid + 512) / 20, kc2 = (tid + 512) % 20, kr3 = ((tid & 255) + 1024) / 20, kc3 = ((tid & 255) + 1024) % 20;
;     const int vd1 = tid >> 3, vc = tid & 7, vd2 = vd1 + 64;
;     ...
;     A_LOAD(0); A_STORE(0);
;     __syncthreads();
;     f32x16 o[4];
; #pragma unroll
;     for (int d = 0; d < 4; ++d)
; #pragma unroll
;         for (int r = 0; r < 16; ++r) o[d][r] = 0.f;
;     float mrun = -1e30f, lrun = 0.f;
;     const int koff = swap23(i) * KT_PITCH + 16 * hi, voff = KT_BYTES + i * VT_PITCH + 16 * hi;
;     for (int t = 0; t < U.nt; ++t) {
;         const bool more = t + 1 < U.nt;
;         if (more) A_LOAD(t + 1);
.LBB0_677:
	s_or_b64 exec, exec, s[10:11]
	s_mov_b32 s3, 0x66666667
	v_mul_hi_i32 v1, v0, s3
	v_lshrrev_b32_e32 v2, 31, v1
	v_ashrrev_i32_e32 v1, 3, v1
	v_add_u32_e32 v1, v1, v2
	v_mul_lo_u32 v2, v1, 20
	v_sub_u32_e32 v16, v0, v2
	v_add_u32_e32 v2, 0x200, v0
	v_mul_hi_i32 v3, v2, s3
	v_lshrrev_b32_e32 v4, 31, v3
	v_ashrrev_i32_e32 v3, 3, v3
	v_add_u32_e32 v17, v3, v4
	v_mul_lo_u32 v3, v17, 20
	v_sub_u32_e32 v18, v2, v3
	s_movk_i32 s3, 0x400
	v_mov_b32_e32 v2, 0xff
	v_bitop3_b16 v2, v0, s3, v2 bitop3:0xec
	s_mov_b32 s3, 0xcccd
	v_mul_u32_u24_sdwa v3, v2, s3 dst_sel:DWORD dst_unused:UNUSED_PAD src0_sel:WORD_0 src1_sel:DWORD
	v_lshrrev_b32_e32 v19, 20, v3
	v_mul_lo_u16_e32 v3, 20, v19
	s_movk_i32 s3, 0xa0
	v_sub_u16_e32 v14, v2, v3
	v_mul_lo_u32 v2, v1, s3
	v_ashrrev_i32_e32 v3, 31, v2
	v_lshlrev_b32_e32 v6, 3, v16
	v_mul_lo_u32 v8, v17, s3
	v_lshlrev_b64 v[2:3], 1, v[2:3]
	v_ashrrev_i32_e32 v7, 31, v6
	v_ashrrev_i32_e32 v9, 31, v8
	v_lshlrev_b32_e32 v12, 3, v18
	v_lshl_add_u64 v[4:5], s[0:1], 0, v[2:3]
	v_lshlrev_b64 v[6:7], 1, v[6:7]
	v_lshlrev_b64 v[8:9], 1, v[8:9]
	v_ashrrev_i32_e32 v13, 31, v12
	v_lshl_add_u64 v[4:5], v[4:5], 0, v[6:7]
	v_lshl_add_u64 v[10:11], s[0:1], 0, v[8:9]
	v_lshlrev_b64 v[12:13], 1, v[12:13]
	v_lshl_add_u64 v[10:11], v[10:11], 0, v[12:13]
	global_load_dwordx4 v[136:139], v[4:5], off
	global_load_dwordx4 v[140:143], v[10:11], off
	v_mul_u32_u24_e32 v4, 0xa0, v19
	v_lshlrev_b32_e32 v4, 1, v4
	v_mov_b32_e32 v5, v157
	v_lshl_add_u64 v[10:11], s[0:1], 0, v[4:5]
	v_lshlrev_b32_e32 v166, 4, v14
	v_mov_b32_e32 v167, v157
	v_ashrrev_i32_e32 v20, 3, v0
	v_lshl_add_u64 v[10:11], v[10:11], 0, v[166:167]
	v_add_u32_e32 v21, 64, v20
	global_load_dwordx4 v[144:147], v[10:11], off
	v_mad_i64_i32 v[10:11], s[10:11], s8, v20, 0
	v_lshlrev_b32_e32 v14, 4, v0
	v_lshl_add_u64 v[10:11], v[10:11], 1, s[6:7]
	v_and_b32_e32 v168, 0x70, v14
	v_mov_b32_e32 v169, v157
	v_mad_i64_i32 v[14:15], s[10:11], s8, v21, 0
	v_lshl_add_u64 v[10:11], v[10:11], 0, v[168:169]
	v_lshl_add_u64 v[14:15], v[14:15], 1, s[6:7]
	v_lshl_add_u64 v[14:15], v[14:15], 0, v[168:169]
	global_load_dwordx4 v[148:151], v[10:11], off
	global_load_dwordx4 v[152:155], v[14:15], off
	v_and_b32_e32 v10, 19, v0
	v_lshlrev_b32_e32 v11, 1, v181
	v_lshrrev_b32_e32 v0, 1, v0
	s_add_u32 s6, s6, 0x80
	s_movk_i32 s3, 0x90
	v_mul_lo_u32 v184, v20, s3
	v_and_b32_e32 v11, 8, v11
	v_and_b32_e32 v0, 4, v0
	s_addc_u32 s7, s7, 0
	s_lshl_b32 s3, s8, 1
	s_movk_i32 s8, 0x150
	v_or3_b32 v0, v10, v11, v0
	v_mul_lo_u32 v186, v1, s8
	v_lshlrev_b32_e32 v190, 4, v16
	v_mul_u32_u24_e32 v187, 0x150, v0
	v_mul_lo_u32 v189, v17, s8
	v_add_u32_e32 v0, v186, v190
	v_lshlrev_b32_e32 v191, 4, v18
	v_mad_u32_u24 v1, v19, s8, v166
	v_add_u32_e32 v14, v184, v168
	v_add_u32_e32 v10, v189, v191
	v_mov_b32_e32 v32, v157
	v_mov_b32_e32 v33, v157
	v_mov_b32_e32 v46, v157
	v_mov_b32_e32 v47, v157
	v_mul_u32_u24_e32 v188, 0x150, v19
	v_mov_b32_e32 v34, v157
	v_mov_b32_e32 v35, v157
	v_mov_b32_e32 v36, v157
	v_mov_b32_e32 v37, v157
	v_mov_b32_e32 v38, v157
	v_mov_b32_e32 v39, v157
	v_mov_b32_e32 v40, v157
	v_mov_b32_e32 v41, v157
	v_mov_b32_e32 v42, v157
	v_mov_b32_e32 v43, v157
	v_mov_b32_e32 v44, v157
	v_mov_b32_e32 v45, v157
	v_mov_b64_e32 v[62:63], v[46:47]
	v_ashrrev_i32_e32 v163, 31, v162
	v_lshlrev_b32_e32 v164, 3, v183
	v_mul_u32_u24_e32 v165, 0x90, v181
	v_add_u32_e32 v185, 0x2400, v184
	v_mov_b64_e32 v[60:61], v[44:45]
	v_mov_b64_e32 v[58:59], v[42:43]
	s_waitcnt vmcnt(4)
	ds_write_b128 v0, v[136:139]
	s_waitcnt vmcnt(3)
	ds_write_b128 v10, v[140:143]
	s_waitcnt vmcnt(2)
	ds_write_b128 v1, v[144:147]
	s_waitcnt vmcnt(1)
	ds_write_b128 v14, v[148:151] offset:21504
	s_waitcnt vmcnt(0)
	ds_write_b128 v14, v[152:155] offset:30720
	v_mad_i64_i32 v[0:1], s[8:9], s3, v20, v[168:169]
	v_lshl_add_u64 v[170:171], s[6:7], 0, v[0:1]
	v_mad_i64_i32 v[0:1], s[8:9], s3, v21, v[168:169]
	v_lshl_add_u64 v[172:173], s[6:7], 0, v[0:1]
	v_lshl_add_u64 v[0:1], v[2:3], 0, v[6:7]
	s_mov_b64 s[6:7], 0x5000
	v_lshl_add_u64 v[174:175], v[0:1], 0, s[6:7]
	v_lshl_add_u64 v[0:1], v[8:9], 0, v[12:13]
	v_lshl_add_u64 v[176:177], v[0:1], 0, s[6:7]
	v_lshl_add_u64 v[0:1], v[4:5], 0, v[166:167]
	v_lshl_add_u64 v[178:179], v[0:1], 0, s[6:7]
	v_mov_b64_e32 v[16:17], v[32:33]
	v_mov_b64_e32 v[0:1], v[32:33]
	s_lshl_b32 s3, s89, 6
	s_mov_b32 s6, 0
	v_mov_b32_e32 v169, 0xf149f2ca
	v_mov_b32_e32 v167, 0
	v_mov_b64_e32 v[56:57], v[40:41]
	v_mov_b64_e32 v[54:55], v[38:39]
	v_mov_b64_e32 v[52:53], v[36:37]
	v_mov_b64_e32 v[50:51], v[34:35]
	v_mov_b64_e32 v[48:49], v[32:33]
	v_mov_b64_e32 v[18:19], v[34:35]
	v_mov_b64_e32 v[20:21], v[36:37]
	v_mov_b64_e32 v[22:23], v[38:39]
	v_mov_b64_e32 v[24:25], v[40:41]
	v_mov_b64_e32 v[26:27], v[42:43]
	v_mov_b64_e32 v[28:29], v[44:45]
	v_mov_b64_e32 v[30:31], v[46:47]
	v_mov_b64_e32 v[2:3], v[34:35]
	v_mov_b64_e32 v[4:5], v[36:37]
	v_mov_b64_e32 v[6:7], v[38:39]
	v_mov_b64_e32 v[8:9], v[40:41]
	v_mov_b64_e32 v[10:11], v[42:43]
	v_mov_b64_e32 v[12:13], v[44:45]
	v_mov_b64_e32 v[14:15], v[46:47]
	s_mov_b32 s7, 0
	s_mov_b64 s[40:41], s[0:1]
	v_add_u32_e32 v216, v186, v190
	v_add_u32_e32 v217, v189, v191
	v_add_u32_e32 v218, v188, v166
	v_add_u32_e32 v219, v184, v168
	v_add_u32_e32 v220, v185, v168
	v_mov_b32_e32 v169, 0
	v_mov_b32_e32 v232, 0
	v_mov_b32_e32 v233, 0
	v_mov_b32_e32 v234, 0
	v_mov_b32_e32 v235, 0
	v_mov_b32_e32 v236, 0
	v_mov_b32_e32 v237, 0
	v_mov_b32_e32 v238, 0
	v_mov_b32_e32 v239, 0
	v_mov_b32_e32 v240, 0
	v_mov_b32_e32 v241, 0
	v_mov_b32_e32 v242, 0
	v_mov_b32_e32 v243, 0
	v_mov_b32_e32 v244, 0
	v_mov_b32_e32 v245, 0
	v_mov_b32_e32 v246, 0
	v_mov_b32_e32 v247, 0
	s_mov_b32 s20, 0
	s_mov_b32 s22, 0
	s_mov_b32 s23, 0x9c00
	s_mov_b32 s24, 0x13800
	s_cmp_gt_u32 s89, 1
	s_cbranch_scc0 .Lattn_pro_noload
	global_load_dwordx4 v[136:139], v174, s[40:41]
	global_load_dwordx4 v[140:143], v176, s[40:41]
	global_load_dwordx4 v[144:147], v178, s[40:41]
	global_load_dwordx4 v[148:151], v[170:171], off
	global_load_dwordx4 v[152:155], v[172:173], off
	s_add_u32 s40, s40, 0x5000
	s_addc_u32 s41, s41, 0
	v_lshl_add_u64 v[170:171], v[170:171], 0, s[82:83]
	v_lshl_add_u64 v[172:173], v[172:173], 0, s[82:83]
.Lattn_pro_noload:
	s_waitcnt lgkmcnt(0)
	s_barrier
	s_cmp_lt_u32 s88, 4
	s_cbranch_scc1 .Lattn_x0
	s_mov_b32 s29, 0x9c00
	s_mov_b32 s30, 2
	s_waitcnt vmcnt(0)
	v_add_u32_e32 v221, s29, v216
	ds_write_b128 v221, v[136:139]
	v_add_u32_e32 v221, s29, v217
	ds_write_b128 v221, v[140:143]
	v_add_u32_e32 v221, s29, v218
	ds_write_b128 v221, v[144:147]
	v_add_u32_e32 v221, s29, v219
	ds_write_b128 v221, v[148:151] offset:21504
	v_add_u32_e32 v221, s29, v220
	ds_write_b128 v221, v[152:155] offset:21504
	s_cmp_lt_u32 s30, s89
	s_cbranch_scc0 .Lattn_noload_entry
	global_load_dwordx4 v[136:139], v174, s[40:41]
	global_load_dwordx4 v[140:143], v176, s[40:41]
	global_load_dwordx4 v[144:147], v178, s[40:41]
	global_load_dwordx4 v[148:151], v[170:171], off
	global_load_dwordx4 v[152:155], v[172:173], off
	s_add_u32 s40, s40, 0x5000
	s_addc_u32 s41, s41, 0
	v_lshl_add_u64 v[170:171], v[170:171], 0, s[82:83]
	v_lshl_add_u64 v[172:173], v[172:173], 0, s[82:83]

; __device__ __forceinline__ void attn_unit(KParams& P, int l, const AUnit& U, LAS unsigned char* lds) {
;     ...
;         if ((t + 1) * 64 > U.kvlen) {
;             const int kb0 = t * 64 + 8 * hi;
; #pragma unroll
;             for (int r = 0; r < 16; ++r) { const int kv = kb0 + 16 * (r >> 3) + (r & 7); if (kv >= U.kvlen) p0[r] = -INFINITY; if (kv + 32 >= U.kvlen) p1[r] = -INFINITY; }
;         }
.Lattn_loop:
	s_barrier
	s_setprio 2
	s_cmp_lt_u32 s88, 4
	s_cselect_b32 s29, s23, s24
	s_cselect_b32 s30, 2, 3
	s_add_i32 s30, s30, s20
	s_waitcnt vmcnt(0)
	v_add_u32_e32 v221, s29, v216
	ds_write_b128 v221, v[136:139]
	v_add_u32_e32 v221, s29, v217
	ds_write_b128 v221, v[140:143]
	v_add_u32_e32 v221, s29, v218
	ds_write_b128 v221, v[144:147]
	v_add_u32_e32 v221, s29, v219
	ds_write_b128 v221, v[148:151] offset:21504
	v_add_u32_e32 v221, s29, v220
	ds_write_b128 v221, v[152:155] offset:21504
	s_cmp_lt_u32 s30, s89
	s_cbranch_scc0 .Lattn_noload_y
	global_load_dwordx4 v[136:139], v174, s[40:41]
	global_load_dwordx4 v[140:143], v176, s[40:41]
	global_load_dwordx4 v[144:147], v178, s[40:41]
	global_load_dwordx4 v[148:151], v[170:171], off
	global_load_dwordx4 v[152:155], v[172:173], off
	s_add_u32 s40, s40, 0x5000
	s_addc_u32 s41, s41, 0
	v_lshl_add_u64 v[170:171], v[170:171], 0, s[82:83]
	v_lshl_add_u64 v[172:173], v[172:173], 0, s[82:83]
.Lattn_noload_y:
	s_nop 7
	s_lshl_b32 s25, s20, 6
	s_add_i32 s28, s25, 64
	s_cmp_le_u32 s28, s70
	s_cbranch_scc1 .Lattn_nomask
	v_add_u32_e32 v208, s25, v164
	v_add_u32_e32 v209, 0, v208
	v_cmp_gt_u32_e32 vcc, s70, v209
	v_cndmask_b32_e32 v80, v225, v80, vcc
	v_add_u32_e32 v209, 32, v208
	v_cmp_gt_u32_e32 vcc, s70, v209
	v_cndmask_b32_e32 v64, v225, v64, vcc
	v_add_u32_e32 v209, 1, v208
	v_cmp_gt_u32_e32 vcc, s70, v209
	v_cndmask_b32_e32 v81, v225, v81, vcc
	v_add_u32_e32 v209, 33, v208
	v_cmp_gt_u32_e32 vcc, s70, v209
	v_cndmask_b32_e32 v65, v225, v65, vcc
	v_add_u32_e32 v209, 2, v208
	v_cmp_gt_u32_e32 vcc, s70, v209
	v_cndmask_b32_e32 v82, v225, v82, vcc
	v_add_u32_e32 v209, 34, v208
	v_cmp_gt_u32_e32 vcc, s70, v209
	v_cndmask_b32_e32 v66, v225, v66, vcc
	v_add_u32_e32 v209, 3, v208
	v_cmp_gt_u32_e32 vcc, s70, v209
	v_cndmask_b32_e32 v83, v225, v83, vcc
	v_add_u32_e32 v209, 35, v208
	v_cmp_gt_u32_e32 vcc, s70, v209
	v_cndmask_b32_e32 v67, v225, v67, vcc
	v_add_u32_e32 v209, 4, v208
	v_cmp_gt_u32_e32 vcc, s70, v209
	v_cndmask_b32_e32 v84, v225, v84, vcc
	v_add_u32_e32 v209, 36, v208
	v_cmp_gt_u32_e32 vcc, s70, v209
	v_cndmask_b32_e32 v68, v225, v68, vcc
	v_add_u32_e32 v209, 5, v208
	v_cmp_gt_u32_e32 vcc, s70, v209
	v_cndmask_b32_e32 v85, v225, v85, vcc
	v_add_u32_e32 v209, 37, v208
	v_cmp_gt_u32_e32 vcc, s70, v209
	v_cndmask_b32_e32 v69, v225, v69, vcc
	v_add_u32_e32 v209, 6, v208
	v_cmp_gt_u32_e32 vcc, s70, v209
	v_cndmask_b32_e32 v86, v225, v86, vcc
	v_add_u32_e32 v209, 38, v208
	v_cmp_gt_u32_e32 vcc, s70, v209
	v_cndmask_b32_e32 v70, v225, v70, vcc
	v_add_u32_e32 v209, 7, v208
	v_cmp_gt_u32_e32 vcc, s70, v209
	v_cndmask_b32_e32 v87, v225, v87, vcc
	v_add_u32_e32 v209, 39, v208
	v_cmp_gt_u32_e32 vcc, s70, v209
	v_cndmask_b32_e32 v71, v225, v71, vcc
	v_add_u32_e32 v209, 16, v208
	v_cmp_gt_u32_e32 vcc, s70, v209
	v_cndmask_b32_e32 v88, v225, v88, vcc
	v_add_u32_e32 v209, 48, v208
	v_cmp_gt_u32_e32 vcc, s70, v209
	v_cndmask_b32_e32 v72, v225, v72, vcc
	v_add_u32_e32 v209, 17, v208
	v_cmp_gt_u32_e32 vcc, s70, v209
	v_cndmask_b32_e32 v89, v225, v89, vcc
	v_add_u32_e32 v209, 49, v208
	v_cmp_gt_u32_e32 vcc, s70, v209
	v_cndmask_b32_e32 v73, v225, v73, vcc
	v_add_u32_e32 v209, 18, v208
	v_cmp_gt_u32_e32 vcc, s70, v209
	v_cndmask_b32_e32 v90, v225, v90, vcc
	v_add_u32_e32 v209, 50, v208
	v_cmp_gt_u32_e32 vcc, s70, v209
	v_cndmask_b32_e32 v74, v225, v74, vcc
	v_add_u32_e32 v209, 19, v208
	v_cmp_gt_u32_e32 vcc, s70, v209
	v_cndmask_b32_e32 v91, v225, v91, vcc
	v_add_u32_e32 v209, 51, v208
	v_cmp_gt_u32_e32 vcc, s70, v209
	v_cndmask_b32_e32 v75, v225, v75, vcc
	v_add_u32_e32 v209, 20, v208
	v_cmp_gt_u32_e32 vcc, s70, v209
	v_cndmask_b32_e32 v92, v225, v92, vcc
	v_add_u32_e32 v209, 52, v208
	v_cmp_gt_u32_e32 vcc, s70, v209
	v_cndmask_b32_e32 v76, v225, v76, vcc
	v_add_u32_e32 v209, 21, v208
	v_cmp_gt_u32_e32 vcc, s70, v209
	v_cndmask_b32_e32 v93, v225, v93, vcc
	v_add_u32_e32 v209, 53, v208
	v_cmp_gt_u32_e32 vcc, s70, v209
	v_cndmask_b32_e32 v77, v225, v77, vcc
	v_add_u32_e32 v209, 22, v208
	v_cmp_gt_u32_e32 vcc, s70, v209
	v_cndmask_b32_e32 v94, v225, v94, vcc
	v_add_u32_e32 v209, 54, v208
	v_cmp_gt_u32_e32 vcc, s70, v209
	v_cndmask_b32_e32 v78, v225, v78, vcc
	v_add_u32_e32 v209, 23, v208
	v_cmp_gt_u32_e32 vcc, s70, v209
	v_cndmask_b32_e32 v95, v225, v95, vcc
	v_add_u32_e32 v209, 55, v208
	v_cmp_gt_u32_e32 vcc, s70, v209
	v_cndmask_b32_e32 v79, v225, v79, vcc

; #define LAS __attribute__((address_space(3)))
; __device__ __forceinline__ unsigned cvt_pk_bf16(float lo, float hi) { f32x2 v = {lo, hi}; bf16x2_t b = __builtin_convertvector(v, bf16x2_t); return __builtin_bit_cast(unsigned, b); }
; __device__ __forceinline__ void attn_unit(KParams& P, int l, const AUnit& U, LAS unsigned char* lds) {
;     ...
;         const float mnew = fmaxf(mrun, mx); const float f = __builtin_amdgcn_exp2f(mrun - mnew); const bool grew = __any(mnew > mrun); mrun = mnew;
;         f32x2 ps2 = {0.f, 0.f}; const f32x2 nm2 = {-mnew, -mnew};
; #pragma unroll
;         for (int r = 0; r < 16; r += 2) { f32x2 a = (f32x2){p0[r], p0[r + 1]} + nm2, b = (f32x2){p1[r], p1[r + 1]} + nm2;
;             a[0] = __builtin_amdgcn_exp2f(a[0]); a[1] = __builtin_amdgcn_exp2f(a[1]); b[0] = __builtin_amdgcn_exp2f(b[0]); b[1] = __builtin_amdgcn_exp2f(b[1]);
;             p0[r] = a[0]; p0[r + 1] = a[1]; p1[r] = b[0]; p1[r + 1] = b[1]; ps2 += a; ps2 += b; }
;         const float ps = ps2[0] + ps2[1];
;         lrun = lrun * f + ps;
;         if (grew) {
; #pragma unroll
;             for (int d = 0; d < 4; ++d)
; #pragma unroll
;                 for (int r = 0; r < 16; ++r) o[d][r] *= f;
;         }
;         bf16x8 pf[4];
;         { u32x4 w;
;           w.x = cvt_pk_bf16(p0[0], p0[1]); w.y = cvt_pk_bf16(p0[2], p0[3]); w.z = cvt_pk_bf16(p0[4], p0[5]); w.w = cvt_pk_bf16(p0[6], p0[7]); pf[0] = __builtin_bit_cast(bf16x8, w);
;           w.x = cvt_pk_bf16(p0[8], p0[9]); w.y = cvt_pk_bf16(p0[10], p0[11]); w.z = cvt_pk_bf16(p0[12], p0[13]); w.w = cvt_pk_bf16(p0[14], p0[15]); pf[1] = __builtin_bit_cast(bf16x8, w);
;           w.x = cvt_pk_bf16(p1[0], p1[1]); w.y = cvt_pk_bf16(p1[2], p1[3]); w.z = cvt_pk_bf16(p1[4], p1[5]); w.w = cvt_pk_bf16(p1[6], p1[7]); pf[2] = __builtin_bit_cast(bf16x8, w);
;           w.x = cvt_pk_bf16(p1[8], p1[9]); w.y = cvt_pk_bf16(p1[10], p1[11]); w.z = cvt_pk_bf16(p1[12], p1[13]); w.w = cvt_pk_bf16(p1[14], p1[15]); pf[3] = __builtin_bit_cast(bf16x8, w); }
; #pragma unroll
;         for (int d = 0; d < 4; ++d)
; #pragma unroll
;             for (int ks = 0; ks < 4; ++ks) {
;                 const bf16x8 vf = *(const LAS bf16x8*)(bb + voff + d * 32 * VT_PITCH + 32 * ks);
.Lattn_resc_common:
	v_sub_f32_e32 v80, v80, v180
	v_sub_f32_e32 v81, v81, v180
	v_sub_f32_e32 v82, v82, v180
	v_sub_f32_e32 v83, v83, v180
	v_sub_f32_e32 v84, v84, v180
	v_sub_f32_e32 v85, v85, v180
	v_sub_f32_e32 v86, v86, v180
	v_sub_f32_e32 v87, v87, v180
	v_sub_f32_e32 v88, v88, v180
	v_sub_f32_e32 v89, v89, v180
	v_sub_f32_e32 v90, v90, v180
	v_sub_f32_e32 v91, v91, v180
	v_sub_f32_e32 v92, v92, v180
	v_sub_f32_e32 v93, v93, v180
	v_sub_f32_e32 v94, v94, v180
	v_sub_f32_e32 v95, v95, v180
	v_sub_f32_e32 v64, v64, v180
	v_sub_f32_e32 v65, v65, v180
	v_sub_f32_e32 v66, v66, v180
	v_sub_f32_e32 v67, v67, v180
	v_sub_f32_e32 v68, v68, v180
	v_sub_f32_e32 v69, v69, v180
	v_sub_f32_e32 v70, v70, v180
	v_sub_f32_e32 v71, v71, v180
	v_sub_f32_e32 v72, v72, v180
	v_sub_f32_e32 v73, v73, v180
	v_sub_f32_e32 v74, v74, v180
	v_sub_f32_e32 v75, v75, v180
	v_sub_f32_e32 v76, v76, v180
	v_sub_f32_e32 v77, v77, v180
	v_sub_f32_e32 v78, v78, v180
	v_sub_f32_e32 v79, v79, v180
	v_add_f32_e32 v169, v169, v180
	v_xor_b32_e32 v232, 0x80000000, v169
	v_xor_b32_e32 v233, 0x80000000, v169
	v_xor_b32_e32 v234, 0x80000000, v169
	v_xor_b32_e32 v235, 0x80000000, v169
	v_xor_b32_e32 v236, 0x80000000, v169
	v_xor_b32_e32 v237, 0x80000000, v169
	v_xor_b32_e32 v238, 0x80000000, v169
	v_xor_b32_e32 v239, 0x80000000, v169
	v_xor_b32_e32 v240, 0x80000000, v169
	v_xor_b32_e32 v241, 0x80000000, v169
	v_xor_b32_e32 v242, 0x80000000, v169
	v_xor_b32_e32 v243, 0x80000000, v169
	v_xor_b32_e32 v244, 0x80000000, v169
	v_xor_b32_e32 v245, 0x80000000, v169
	v_xor_b32_e32 v246, 0x80000000, v169
	v_xor_b32_e32 v247, 0x80000000, v169
.Lattn_fast:
	v_exp_f32_e32 v80, v80
	v_exp_f32_e32 v81, v81
	v_exp_f32_e32 v82, v82
	v_exp_f32_e32 v83, v83
	v_exp_f32_e32 v84, v84
	v_exp_f32_e32 v85, v85
	v_exp_f32_e32 v86, v86
	v_exp_f32_e32 v87, v87
	v_exp_f32_e32 v88, v88
	v_exp_f32_e32 v89, v89
	v_exp_f32_e32 v90, v90
	v_exp_f32_e32 v91, v91
	v_exp_f32_e32 v92, v92
	v_exp_f32_e32 v93, v93
	v_exp_f32_e32 v94, v94
	v_exp_f32_e32 v95, v95
	v_add_f32_e32 v208, v80, v81
	v_add_f32_e32 v208, v208, v82
	v_add_f32_e32 v208, v208, v83
	v_add_f32_e32 v208, v208, v84
	v_add_f32_e32 v208, v208, v85
	v_add_f32_e32 v208, v208, v86
	v_add_f32_e32 v208, v208, v87
	v_exp_f32_e32 v64, v64
	v_exp_f32_e32 v65, v65
	v_exp_f32_e32 v66, v66
	v_exp_f32_e32 v67, v67
	v_exp_f32_e32 v68, v68
	v_exp_f32_e32 v69, v69
	v_exp_f32_e32 v70, v70
	v_exp_f32_e32 v71, v71
	v_add_f32_e32 v209, v88, v89
	v_add_f32_e32 v209, v209, v90
	v_add_f32_e32 v209, v209, v91
	v_add_f32_e32 v209, v209, v92
	v_add_f32_e32 v209, v209, v93
	v_add_f32_e32 v209, v209, v94
	v_add_f32_e32 v209, v209, v95
	v_cvt_pk_bf16_f32 v80, v80, v81
	v_cvt_pk_bf16_f32 v81, v82, v83
	v_cvt_pk_bf16_f32 v82, v84, v85
	v_cvt_pk_bf16_f32 v83, v86, v87
	v_exp_f32_e32 v72, v72
	v_exp_f32_e32 v73, v73
	v_exp_f32_e32 v74, v74
	v_exp_f32_e32 v75, v75
	v_exp_f32_e32 v76, v76
	v_exp_f32_e32 v77, v77
	v_exp_f32_e32 v78, v78
	v_exp_f32_e32 v79, v79
	v_add_f32_e32 v210, v64, v65
	v_add_f32_e32 v210, v210, v66
	v_add_f32_e32 v210, v210, v67
	v_add_f32_e32 v210, v210, v68
	v_add_f32_e32 v210, v210, v69
	v_add_f32_e32 v210, v210, v70
	v_add_f32_e32 v210, v210, v71
	v_cvt_pk_bf16_f32 v84, v88, v89
	v_cvt_pk_bf16_f32 v85, v90, v91
	v_cvt_pk_bf16_f32 v86, v92, v93
	v_cvt_pk_bf16_f32 v87, v94, v95
	v_add_f32_e32 v211, v72, v73
	v_add_f32_e32 v211, v211, v74
	v_add_f32_e32 v211, v211, v75
	v_add_f32_e32 v211, v211, v76
	v_add_f32_e32 v211, v211, v77
	v_add_f32_e32 v211, v211, v78
	v_add_f32_e32 v211, v211, v79
	v_cvt_pk_bf16_f32 v64, v64, v65
	v_cvt_pk_bf16_f32 v65, v66, v67
	v_cvt_pk_bf16_f32 v66, v68, v69
	v_cvt_pk_bf16_f32 v67, v70, v71
	v_cvt_pk_bf16_f32 v68, v72, v73
	v_cvt_pk_bf16_f32 v69, v74, v75
	v_cvt_pk_bf16_f32 v70, v76, v77
	v_cvt_pk_bf16_f32 v71, v78, v79
	v_add_f32_e32 v208, v208, v209
	v_add_f32_e32 v210, v210, v211
	v_add_f32_e32 v208, v208, v210
	v_add_f32_e32 v167, v167, v208
	s_waitcnt lgkmcnt(0)
	v_add3_u32 v231, s22, v165, v156
	ds_read_b128 v[192:195], v231 offset:21504
	ds_read_b128 v[196:199], v231 offset:21536
	ds_read_b128 v[200:203], v231 offset:21568
	ds_read_b128 v[204:207], v231 offset:21600
	ds_read_b128 v[208:211], v231 offset:26112
	ds_read_b128 v[226:229], v231 offset:26144
	s_setprio 0
	s_barrier
	s_add_i32 s25, s20, 1
	s_cmp_lt_u32 s25, s89
	s_cbranch_scc0 .Lattn_xlast
; #define LAS __attribute__((address_space(3)))
; __device__ __forceinline__ void attn_unit(KParams& P, int l, const AUnit& U, LAS unsigned char* lds) {
;     ...
;         for (int s = 0; s < 10; ++s) {
;             const bf16x8 k0 = *(const LAS bf16x8*)(bb + koff + 32 * s), k1 = *(const LAS bf16x8*)(bb + koff + 32 * KT_PITCH + 32 * s);
;             p0 = __builtin_amdgcn_mfma_f32_32x32x16_bf16(k0, qf[s], p0, 0, 0, 0);
;             p1 = __builtin_amdgcn_mfma_f32_32x32x16_bf16(k1, qf[s], p1, 0, 0, 0);
;         }
;     ...
; #pragma unroll
;         for (int d = 0; d < 4; ++d)
; #pragma unroll
;             for (int ks = 0; ks < 4; ++ks) {
;                 const bf16x8 vf = *(const LAS bf16x8*)(bb + voff + d * 32 * VT_PITCH + 32 * ks);
;                 o[d] = __builtin_amdgcn_mfma_f32_32x32x16_bf16(vf, pf[ks], o[d], 0, 0, 0);
;             }
	v_add3_u32 v230, s23, v187, v156
	s_waitcnt lgkmcnt(5)
	v_mfma_f32_32x32x16_bf16 v[48:63], v[192:195], v[80:83], v[48:63]
	ds_read_b128 v[248:251], v231 offset:26176
	s_waitcnt lgkmcnt(5)
	v_mfma_f32_32x32x16_bf16 v[48:63], v[196:199], v[84:87], v[48:63]
	ds_read_b128 v[192:195], v231 offset:26208
	s_waitcnt lgkmcnt(5)
	v_mfma_f32_32x32x16_bf16 v[48:63], v[200:203], v[64:67], v[48:63]
	ds_read_b128 v[196:199], v231 offset:30720
	s_waitcnt lgkmcnt(5)
	v_mfma_f32_32x32x16_bf16 v[48:63], v[204:207], v[68:71], v[48:63]
	ds_read_b128 v[200:203], v231 offset:30752
	s_waitcnt lgkmcnt(5)
	v_mfma_f32_32x32x16_bf16 v[32:47], v[208:211], v[80:83], v[32:47]
	ds_read_b128 v[204:207], v231 offset:30784
	s_waitcnt lgkmcnt(5)
	v_mfma_f32_32x32x16_bf16 v[32:47], v[226:229], v[84:87], v[32:47]
	ds_read_b128 v[208:211], v231 offset:30816
	s_waitcnt lgkmcnt(5)
	v_mfma_f32_32x32x16_bf16 v[32:47], v[248:251], v[64:67], v[32:47]
	ds_read_b128 v[226:229], v231 offset:35328
	s_waitcnt lgkmcnt(5)
	v_mfma_f32_32x32x16_bf16 v[32:47], v[192:195], v[68:71], v[32:47]
	ds_read_b128 v[248:251], v231 offset:35360
	s_waitcnt lgkmcnt(5)
	v_mfma_f32_32x32x16_bf16 v[16:31], v[196:199], v[80:83], v[16:31]
	ds_read_b128 v[192:195], v231 offset:35392
	s_waitcnt lgkmcnt(5)
	v_mfma_f32_32x32x16_bf16 v[16:31], v[200:203], v[84:87], v[16:31]
	ds_read_b128 v[196:199], v231 offset:35424
	s_waitcnt lgkmcnt(5)
	v_mfma_f32_32x32x16_bf16 v[16:31], v[204:207], v[64:67], v[16:31]
	ds_read_b128 v[200:203], v230
	s_waitcnt lgkmcnt(5)
	v_mfma_f32_32x32x16_bf16 v[16:31], v[208:211], v[68:71], v[16:31]
	ds_read_b128 v[204:207], v230 offset:10752
	s_waitcnt lgkmcnt(5)
	v_mfma_f32_32x32x16_bf16 v[0:15], v[226:229], v[80:83], v[0:15]
	ds_read_b128 v[208:211], v230 offset:32
	s_waitcnt lgkmcnt(5)
	v_mfma_f32_32x32x16_bf16 v[0:15], v[248:251], v[84:87], v[0:15]
	ds_read_b128 v[226:229], v230 offset:10784
	s_waitcnt lgkmcnt(5)
	v_mfma_f32_32x32x16_bf16 v[0:15], v[192:195], v[64:67], v[0:15]
	ds_read_b128 v[248:251], v230 offset:64
	s_waitcnt lgkmcnt(5)
	v_mfma_f32_32x32x16_bf16 v[0:15], v[196:199], v[68:71], v[0:15]
	ds_read_b128 v[192:195], v230 offset:10816
	s_waitcnt lgkmcnt(5)
	v_mfma_f32_32x32x16_bf16 v[80:95], v[200:203], v[96:99], v[232:247]
	ds_read_b128 v[196:199], v230 offset:96
	s_waitcnt lgkmcnt(5)
	v_mfma_f32_32x32x16_bf16 v[64:79], v[204:207], v[96:99], v[232:247]
	ds_read_b128 v[200:203], v230 offset:10848
	s_waitcnt lgkmcnt(5)
	v_mfma_f32_32x32x16_bf16 v[80:95], v[208:211], v[100:103], v[80:95]
	ds_read_b128 v[204:207], v230 offset:128
	s_waitcnt lgkmcnt(5)
	v_mfma_f32_32x32x16_bf16 v[64:79], v[226:229], v[100:103], v[64:79]
	ds_read_b128 v[208:211], v230 offset:10880
	s_waitcnt lgkmcnt(5)
	v_mfma_f32_32x32x16_bf16 v[80:95], v[248:251], v[104:107], v[80:95]
	ds_read_b128 v[226:229], v230 offset:160
	s_waitcnt lgkmcnt(5)
	v_mfma_f32_32x32x16_bf16 v[64:79], v[192:195], v[104:107], v[64:79]
	ds_read_b128 v[248:251], v230 offset:10912
	s_waitcnt lgkmcnt(5)
	v_mfma_f32_32x32x16_bf16 v[80:95], v[196:199], v[108:111], v[80:95]
	ds_read_b128 v[192:195], v230 offset:192
	s_waitcnt lgkmcnt(5)
	v_mfma_f32_32x32x16_bf16 v[64:79], v[200:203], v[108:111], v[64:79]
	ds_read_b128 v[196:199], v230 offset:10944
	s_waitcnt lgkmcnt(5)
	v_mfma_f32_32x32x16_bf16 v[80:95], v[204:207], v[112:115], v[80:95]
	ds_read_b128 v[200:203], v230 offset:224
	s_waitcnt lgkmcnt(5)
	v_mfma_f32_32x32x16_bf16 v[64:79], v[208:211], v[112:115], v[64:79]
	ds_read_b128 v[204:207], v230 offset:10976
	s_waitcnt lgkmcnt(5)
	v_mfma_f32_32x32x16_bf16 v[80:95], v[226:229], v[116:119], v[80:95]
	ds_read_b128 v[208:211], v230 offset:256
	s_waitcnt lgkmcnt(5)
	v_mfma_f32_32x32x16_bf16 v[64:79], v[248:251], v[116:119], v[64:79]
	ds_read_b128 v[226:229], v230 offset:11008
	s_waitcnt lgkmcnt(5)
	v_mfma_f32_32x32x16_bf16 v[80:95], v[192:195], v[120:123], v[80:95]
	ds_read_b128 v[248:251], v230 offset:288
	s_waitcnt lgkmcnt(5)
	v_mfma_f32_32x32x16_bf16 v[64:79], v[196:199], v[120:123], v[64:79]
	ds_read_b128 v[192:195], v230 offset:11040
	s_waitcnt lgkmcnt(5)
	v_mfma_f32_32x32x16_bf16 v[80:95], v[200:203], v[124:127], v[80:95]
	s_waitcnt lgkmcnt(4)
	v_mfma_f32_32x32x16_bf16 v[64:79], v[204:207], v[124:127], v[64:79]
	s_waitcnt lgkmcnt(3)
	v_mfma_f32_32x32x16_bf16 v[80:95], v[208:211], v[128:131], v[80:95]
	s_waitcnt lgkmcnt(2)
	v_mfma_f32_32x32x16_bf16 v[64:79], v[226:229], v[128:131], v[64:79]
	s_waitcnt lgkmcnt(1)
	v_mfma_f32_32x32x16_bf16 v[80:95], v[248:251], v[132:135], v[80:95]
	s_waitcnt lgkmcnt(0)
	v_mfma_f32_32x32x16_bf16 v[64:79], v[192:195], v[132:135], v[64:79]
	s_waitcnt lgkmcnt(0)
	s_mov_b32 s25, s22
	s_mov_b32 s22, s23
	s_mov_b32 s23, s24
	s_mov_b32 s24, s25
	s_add_i32 s20, s20, 1
	s_branch .Lattn_loop
